# attention: s_setprio 1 around the QK and PV matrix segments of the key-tile loop (timing-only)
# baseline (speedup 1.0000x reference)
.LBB0_628:
	s_setprio 1
	ds_read_b128 v[66:69], v198
	ds_read_b128 v[204:207], v198 offset:32
	s_add_i32 s6, s72, 0xffffff80
	s_and_b32 s0, s78, 3
	s_cmp_eq_u32 s0, 0
	s_cselect_b64 s[0:1], -1, 0
	s_cmp_ge_u32 s6, s71
	s_cselect_b64 s[4:5], -1, 0
	s_or_b64 s[94:95], s[0:1], s[4:5]
	s_waitcnt lgkmcnt(1)
	v_mfma_f32_32x32x16_bf16 v[114:129], v[66:69], v[130:133], 0
	s_cmp_gt_i32 s6, -1
	s_mov_b64 s[0:1], -1
	s_cselect_b64 s[92:93], -1, 0
	s_and_b64 vcc, exec, s[94:95]
	v_mfma_f32_32x32x16_bf16 v[82:97], v[66:69], v[146:149], 0
	ds_read_b128 v[66:69], v198 offset:4608
	s_waitcnt lgkmcnt(1)
	v_mfma_f32_32x32x16_bf16 v[114:129], v[204:207], v[134:137], v[114:129]
	v_mfma_f32_32x32x16_bf16 v[82:97], v[204:207], v[150:153], v[82:97]
	ds_read_b128 v[204:207], v198 offset:4640
	s_waitcnt lgkmcnt(1)
	v_mfma_f32_32x32x16_bf16 v[98:113], v[66:69], v[130:133], 0
	v_mfma_f32_32x32x16_bf16 v[66:81], v[66:69], v[146:149], 0
	s_waitcnt lgkmcnt(0)
	v_mfma_f32_32x32x16_bf16 v[98:113], v[204:207], v[134:137], v[98:113]
	v_mfma_f32_32x32x16_bf16 v[66:81], v[204:207], v[150:153], v[66:81]
	ds_read_b128 v[204:207], v198 offset:64
	s_waitcnt lgkmcnt(0)
	v_mfma_f32_32x32x16_bf16 v[114:129], v[204:207], v[138:141], v[114:129]
	v_mfma_f32_32x32x16_bf16 v[82:97], v[204:207], v[154:157], v[82:97]
	ds_read_b128 v[204:207], v198 offset:4672
	s_waitcnt lgkmcnt(0)
	v_mfma_f32_32x32x16_bf16 v[98:113], v[204:207], v[138:141], v[98:113]
	v_mfma_f32_32x32x16_bf16 v[66:81], v[204:207], v[154:157], v[66:81]
	ds_read_b128 v[204:207], v198 offset:96
	s_waitcnt lgkmcnt(0)
	v_mfma_f32_32x32x16_bf16 v[114:129], v[204:207], v[142:145], v[114:129]
	v_mfma_f32_32x32x16_bf16 v[82:97], v[204:207], v[158:161], v[82:97]
	ds_read_b128 v[204:207], v198 offset:4704
	s_waitcnt lgkmcnt(0)
	v_mfma_f32_32x32x16_bf16 v[98:113], v[204:207], v[142:145], v[98:113]
	v_mfma_f32_32x32x16_bf16 v[66:81], v[204:207], v[158:161], v[66:81]
	s_setprio 0
	s_cbranch_vccnz .LBB0_630
	s_mov_b32 s0, 0xf149f2ca
	s_nop 4
	v_max3_f32 v201, v114, s0, v115
	v_max3_f32 v201, v201, v116, v117
	v_max3_f32 v201, v201, v118, v119
	v_max3_f32 v201, v201, v120, v121
	v_max3_f32 v201, v201, v122, v123
	v_max3_f32 v201, v201, v124, v125
	v_max3_f32 v201, v201, v126, v127
	v_max3_f32 v201, v201, v128, v129
	v_max3_f32 v201, v201, v98, v99
	v_max3_f32 v201, v201, v100, v101
	v_max3_f32 v201, v201, v102, v103
	v_max3_f32 v201, v201, v104, v105
	v_max3_f32 v201, v201, v106, v107
	v_max3_f32 v201, v201, v108, v109
	v_max3_f32 v201, v201, v110, v111
	v_max3_f32 v201, v201, v112, v113
	s_mov_b64 s[0:1], 0

.LBB0_640:
	s_setprio 1
	ds_read_b128 v[70:73], v196
	ds_read_b128 v[74:77], v173
	ds_read_b128 v[78:81], v174
	s_waitcnt lgkmcnt(4)
	v_add_f32_e32 v67, v67, v68
	v_fmac_f32_e32 v67, v1, v66
	v_add_f32_e32 v1, v99, v100
	s_waitcnt lgkmcnt(1)
	v_mfma_f32_32x32x16_bf16 v[50:65], v[70:73], v[74:77], v[50:65]
	s_add_i32 s78, s78, 1
	s_sub_i32 s74, s74, 64
	s_add_i32 s72, s72, 64
	v_fmac_f32_e32 v1, v199, v98
	v_add_u32_e32 v198, 0x2400, v198
	s_cmpk_eq_i32 s74, 0xfec0
	s_waitcnt lgkmcnt(0)
	v_mfma_f32_32x32x16_bf16 v[18:33], v[70:73], v[78:81], v[18:33]
	ds_read_b128 v[70:73], v197
	s_waitcnt lgkmcnt(0)
	v_mfma_f32_32x32x16_bf16 v[34:49], v[70:73], v[74:77], v[34:49]
	v_mfma_f32_32x32x16_bf16 v[2:17], v[70:73], v[78:81], v[2:17]
	ds_read_b128 v[70:73], v196 offset:32
	ds_read_b128 v[74:77], v173 offset:32
	ds_read_b128 v[78:81], v174 offset:32
	s_waitcnt lgkmcnt(1)
	v_mfma_f32_32x32x16_bf16 v[50:65], v[70:73], v[74:77], v[50:65]
	s_waitcnt lgkmcnt(0)
	v_mfma_f32_32x32x16_bf16 v[18:33], v[70:73], v[78:81], v[18:33]
	ds_read_b128 v[70:73], v197 offset:32
	s_waitcnt lgkmcnt(0)
	v_mfma_f32_32x32x16_bf16 v[34:49], v[70:73], v[74:77], v[34:49]
	v_mfma_f32_32x32x16_bf16 v[2:17], v[70:73], v[78:81], v[2:17]
	ds_read_b128 v[70:73], v196 offset:64
	ds_read_b128 v[74:77], v173 offset:64
	ds_read_b128 v[78:81], v174 offset:64
	s_waitcnt lgkmcnt(1)
	v_mfma_f32_32x32x16_bf16 v[50:65], v[70:73], v[74:77], v[50:65]
	s_waitcnt lgkmcnt(0)
	v_mfma_f32_32x32x16_bf16 v[18:33], v[70:73], v[78:81], v[18:33]
	ds_read_b128 v[70:73], v197 offset:64
	s_waitcnt lgkmcnt(0)
	v_mfma_f32_32x32x16_bf16 v[34:49], v[70:73], v[74:77], v[34:49]
	v_mfma_f32_32x32x16_bf16 v[2:17], v[70:73], v[78:81], v[2:17]
	ds_read_b128 v[70:73], v196 offset:96
	ds_read_b128 v[74:77], v173 offset:96
	ds_read_b128 v[78:81], v174 offset:96
	v_add_u32_e32 v196, 0x80, v196
	s_waitcnt lgkmcnt(1)
	v_mfma_f32_32x32x16_bf16 v[50:65], v[70:73], v[74:77], v[50:65]
	s_waitcnt lgkmcnt(0)
	v_mfma_f32_32x32x16_bf16 v[18:33], v[70:73], v[78:81], v[18:33]
	ds_read_b128 v[70:73], v197 offset:96
	v_add_u32_e32 v197, 0x80, v197
	s_waitcnt lgkmcnt(0)
	v_mfma_f32_32x32x16_bf16 v[34:49], v[70:73], v[74:77], v[34:49]
	v_mfma_f32_32x32x16_bf16 v[2:17], v[70:73], v[78:81], v[2:17]
	s_setprio 0
	s_cbranch_scc1 .LBB0_642
	v_mov_b32_e32 v199, v1
	v_mov_b32_e32 v1, v67
	v_mov_b32_e32 v202, v201
	v_mov_b32_e32 v200, v101
	s_branch .LBB0_628

.LBB0_2210:
	s_setprio 1
	ds_read_b128 v[66:69], v198
	ds_read_b128 v[204:207], v198 offset:32
	s_add_i32 s6, s72, 0xffffff80
	s_and_b32 s0, s94, 3
	s_cmp_eq_u32 s0, 0
	s_cselect_b64 s[0:1], -1, 0
	s_cmp_ge_u32 s6, s71
	s_cselect_b64 s[4:5], -1, 0
	s_or_b64 s[92:93], s[0:1], s[4:5]
	s_waitcnt lgkmcnt(1)
	v_mfma_f32_32x32x16_bf16 v[114:129], v[66:69], v[130:133], 0
	s_cmp_gt_i32 s6, -1
	s_mov_b64 s[0:1], -1
	s_cselect_b64 s[86:87], -1, 0
	s_and_b64 vcc, exec, s[92:93]
	v_mfma_f32_32x32x16_bf16 v[82:97], v[66:69], v[146:149], 0
	ds_read_b128 v[66:69], v198 offset:4608
	s_waitcnt lgkmcnt(1)
	v_mfma_f32_32x32x16_bf16 v[114:129], v[204:207], v[134:137], v[114:129]
	v_mfma_f32_32x32x16_bf16 v[82:97], v[204:207], v[150:153], v[82:97]
	ds_read_b128 v[204:207], v198 offset:4640
	s_waitcnt lgkmcnt(1)
	v_mfma_f32_32x32x16_bf16 v[98:113], v[66:69], v[130:133], 0
	v_mfma_f32_32x32x16_bf16 v[66:81], v[66:69], v[146:149], 0
	s_waitcnt lgkmcnt(0)
	v_mfma_f32_32x32x16_bf16 v[98:113], v[204:207], v[134:137], v[98:113]
	v_mfma_f32_32x32x16_bf16 v[66:81], v[204:207], v[150:153], v[66:81]
	ds_read_b128 v[204:207], v198 offset:64
	s_waitcnt lgkmcnt(0)
	v_mfma_f32_32x32x16_bf16 v[114:129], v[204:207], v[138:141], v[114:129]
	v_mfma_f32_32x32x16_bf16 v[82:97], v[204:207], v[154:157], v[82:97]
	ds_read_b128 v[204:207], v198 offset:4672
	s_waitcnt lgkmcnt(0)
	v_mfma_f32_32x32x16_bf16 v[98:113], v[204:207], v[138:141], v[98:113]
	v_mfma_f32_32x32x16_bf16 v[66:81], v[204:207], v[154:157], v[66:81]
	ds_read_b128 v[204:207], v198 offset:96
	s_waitcnt lgkmcnt(0)
	v_mfma_f32_32x32x16_bf16 v[114:129], v[204:207], v[142:145], v[114:129]
	v_mfma_f32_32x32x16_bf16 v[82:97], v[204:207], v[158:161], v[82:97]
	ds_read_b128 v[204:207], v198 offset:4704
	s_waitcnt lgkmcnt(0)
	v_mfma_f32_32x32x16_bf16 v[98:113], v[204:207], v[142:145], v[98:113]
	v_mfma_f32_32x32x16_bf16 v[66:81], v[204:207], v[158:161], v[66:81]
	s_setprio 0
	s_cbranch_vccnz .LBB0_2212
	s_mov_b32 s0, 0xf149f2ca
	s_nop 4
	v_max3_f32 v201, v114, s0, v115
	v_max3_f32 v201, v201, v116, v117
	v_max3_f32 v201, v201, v118, v119
	v_max3_f32 v201, v201, v120, v121
	v_max3_f32 v201, v201, v122, v123
	v_max3_f32 v201, v201, v124, v125
	v_max3_f32 v201, v201, v126, v127
	v_max3_f32 v201, v201, v128, v129
	v_max3_f32 v201, v201, v98, v99
	v_max3_f32 v201, v201, v100, v101
	v_max3_f32 v201, v201, v102, v103
	v_max3_f32 v201, v201, v104, v105
	v_max3_f32 v201, v201, v106, v107
	v_max3_f32 v201, v201, v108, v109
	v_max3_f32 v201, v201, v110, v111
	v_max3_f32 v201, v201, v112, v113
	s_mov_b64 s[0:1], 0

.LBB0_2222:
	s_setprio 1
	ds_read_b128 v[70:73], v196
	ds_read_b128 v[74:77], v173
	ds_read_b128 v[78:81], v174
	s_waitcnt lgkmcnt(4)
	v_add_f32_e32 v67, v67, v68
	v_fmac_f32_e32 v67, v1, v66
	v_add_f32_e32 v1, v99, v100
	s_waitcnt lgkmcnt(1)
	v_mfma_f32_32x32x16_bf16 v[50:65], v[70:73], v[74:77], v[50:65]
	s_add_i32 s94, s94, 1
	s_sub_i32 s79, s79, 64
	s_add_i32 s72, s72, 64
	v_fmac_f32_e32 v1, v199, v98
	v_add_u32_e32 v198, 0x2400, v198
	s_cmpk_eq_i32 s79, 0xfec0
	s_waitcnt lgkmcnt(0)
	v_mfma_f32_32x32x16_bf16 v[18:33], v[70:73], v[78:81], v[18:33]
	ds_read_b128 v[70:73], v197
	s_waitcnt lgkmcnt(0)
	v_mfma_f32_32x32x16_bf16 v[34:49], v[70:73], v[74:77], v[34:49]
	v_mfma_f32_32x32x16_bf16 v[2:17], v[70:73], v[78:81], v[2:17]
	ds_read_b128 v[70:73], v196 offset:32
	ds_read_b128 v[74:77], v173 offset:32
	ds_read_b128 v[78:81], v174 offset:32
	s_waitcnt lgkmcnt(1)
	v_mfma_f32_32x32x16_bf16 v[50:65], v[70:73], v[74:77], v[50:65]
	s_waitcnt lgkmcnt(0)
	v_mfma_f32_32x32x16_bf16 v[18:33], v[70:73], v[78:81], v[18:33]
	ds_read_b128 v[70:73], v197 offset:32
	s_waitcnt lgkmcnt(0)
	v_mfma_f32_32x32x16_bf16 v[34:49], v[70:73], v[74:77], v[34:49]
	v_mfma_f32_32x32x16_bf16 v[2:17], v[70:73], v[78:81], v[2:17]
	ds_read_b128 v[70:73], v196 offset:64
	ds_read_b128 v[74:77], v173 offset:64
	ds_read_b128 v[78:81], v174 offset:64
	s_waitcnt lgkmcnt(1)
	v_mfma_f32_32x32x16_bf16 v[50:65], v[70:73], v[74:77], v[50:65]
	s_waitcnt lgkmcnt(0)
	v_mfma_f32_32x32x16_bf16 v[18:33], v[70:73], v[78:81], v[18:33]
	ds_read_b128 v[70:73], v197 offset:64
	s_waitcnt lgkmcnt(0)
	v_mfma_f32_32x32x16_bf16 v[34:49], v[70:73], v[74:77], v[34:49]
	v_mfma_f32_32x32x16_bf16 v[2:17], v[70:73], v[78:81], v[2:17]
	ds_read_b128 v[70:73], v196 offset:96
	ds_read_b128 v[74:77], v173 offset:96
	ds_read_b128 v[78:81], v174 offset:96
	v_add_u32_e32 v196, 0x80, v196
	s_waitcnt lgkmcnt(1)
	v_mfma_f32_32x32x16_bf16 v[50:65], v[70:73], v[74:77], v[50:65]
	s_waitcnt lgkmcnt(0)
	v_mfma_f32_32x32x16_bf16 v[18:33], v[70:73], v[78:81], v[18:33]
	ds_read_b128 v[70:73], v197 offset:96
	v_add_u32_e32 v197, 0x80, v197
	s_waitcnt lgkmcnt(0)
	v_mfma_f32_32x32x16_bf16 v[34:49], v[70:73], v[74:77], v[34:49]
	v_mfma_f32_32x32x16_bf16 v[2:17], v[70:73], v[78:81], v[2:17]
	s_setprio 0
	s_cbranch_scc1 .LBB0_2224
	v_mov_b32_e32 v199, v1
	v_mov_b32_e32 v1, v67
	v_mov_b32_e32 v202, v201
	v_mov_b32_e32 v200, v101
	s_branch .LBB0_2210
